# stack of 6 latency de-serialisation edits (SWA bias straight-line, SWA loads hoisted, fill_rstd split, FoX queue pop ahead, forget-bias loaded once, census loads batched)
# baseline (speedup 1.0000x reference)
.LBB0_239:
	v_readlane_b32 s2, v252, 57
	v_readlane_b32 s3, v252, 58
	s_mov_b64 s[10:11], -1
	s_mov_b64 s[12:13], -1
	s_nop 4
	global_load_dword v0, v1, s[2:3] sc1
	v_readlane_b32 s2, v252, 59
	v_readlane_b32 s3, v252, 60
	s_waitcnt lgkmcnt(0)
	s_nop 3
	global_load_dword v2, v1, s[2:3] sc1
	v_readlane_b32 s2, v252, 61
	v_readlane_b32 s3, v252, 62
	s_nop 4
	global_load_dword v3, v1, s[2:3] sc1
	v_readlane_b32 s2, v252, 63
	v_readlane_b32 s3, v253, 0
	s_nop 4
	global_load_dword v4, v1, s[2:3] sc1
	v_readlane_b32 s2, v253, 1
	v_readlane_b32 s3, v253, 2
	s_nop 4
	global_load_dword v5, v1, s[2:3] sc1
	v_readlane_b32 s2, v253, 3
	v_readlane_b32 s3, v253, 4
	s_nop 4
	global_load_dword v6, v1, s[2:3] sc1
	v_readlane_b32 s2, v253, 5
	v_readlane_b32 s3, v253, 6
	s_nop 4
	global_load_dword v7, v1, s[2:3] sc1
	v_readlane_b32 s2, v253, 7
	v_readlane_b32 s3, v253, 8
	s_nop 4
	global_load_dword v8, v1, s[2:3] sc1
	v_readlane_b32 s2, v253, 9
	v_readlane_b32 s3, v253, 10
	s_nop 4
	global_load_dword v9, v1, s[2:3] sc1
	v_readlane_b32 s2, v253, 11
	v_readlane_b32 s3, v253, 12
	s_nop 4
	global_load_dword v10, v1, s[2:3] sc1
	v_readlane_b32 s2, v253, 13
	v_readlane_b32 s3, v253, 14
	s_nop 4
	global_load_dword v11, v1, s[2:3] sc1
	v_readlane_b32 s2, v253, 15
	v_readlane_b32 s3, v253, 16
	s_nop 4
	global_load_dword v12, v1, s[2:3] sc1
	v_readlane_b32 s2, v253, 17
	v_readlane_b32 s3, v253, 18
	s_nop 4
	global_load_dword v13, v1, s[2:3] sc1
	v_readlane_b32 s2, v253, 19
	v_readlane_b32 s3, v253, 20
	s_nop 4
	global_load_dword v14, v1, s[2:3] sc1
	v_readlane_b32 s2, v253, 21
	v_readlane_b32 s3, v253, 22
	s_nop 4
	global_load_dword v15, v1, s[2:3] sc1
	v_readlane_b32 s2, v253, 23
	v_readlane_b32 s3, v253, 24
	s_nop 4
	global_load_dword v16, v1, s[2:3] sc1
	s_waitcnt vmcnt(0)
	v_add_u32_e32 v17, v2, v0
	v_add_u32_e32 v17, v17, v3
	v_add_u32_e32 v17, v17, v4
	v_add_u32_e32 v17, v17, v5
	v_add_u32_e32 v17, v17, v6
	v_add_u32_e32 v17, v17, v7
	v_add_u32_e32 v17, v17, v8
	v_add_u32_e32 v17, v17, v9
	v_add_u32_e32 v17, v17, v10
	v_add_u32_e32 v17, v17, v11
	v_add_u32_e32 v17, v17, v12
	v_add_u32_e32 v17, v17, v13
	v_add_u32_e32 v17, v17, v14
	v_add_u32_e32 v17, v17, v15
	v_add_u32_e32 v17, v17, v16
	v_cmp_eq_u32_e32 vcc, s79, v17
	s_cbranch_vccnz .LBB0_238
	s_and_b32 s2, s0, 0xff
	s_cmp_eq_u32 s2, 0
	s_mov_b64 s[14:15], -1
	s_sleep 1
	s_cbranch_scc1 .LBB0_243
	s_and_b64 vcc, exec, s[14:15]
	s_cbranch_vccz .LBB0_238
